# attention: only the P.V fragment reads pipelined (K.Q^T chain left as compiled)
# baseline (speedup 1.0000x reference)
; #define LAS __attribute__((address_space(3)))
; __device__ __forceinline__ void attn_unit(int b, int h, int qb, const bf16_t* __restrict__ QK, const bf16_t* __restrict__ VT, bf16_t* __restrict__ O, const float* __restrict__ qg, const float* __restrict__ kg, ...
;     ...
;         if (kt > 0) { const int kn = kt - 1; sk0 = *(const u32x4*)(kg0 + (size_t)kn * 64 * 4096); sk1 = *(const u32x4*)(kg1 + (size_t)kn * 64 * 4096); sv0 = *(const u32x4*)(vg0 + kn * 64); sv1 = *(const u32x4*)(vg1 + kn * 64); }
;         if (!wdone && kt * 64 < q0 + wid * 32 + 31) {
;             const LAS unsigned char* kb_ = Kb + buf * AK_BUF + kfo; const LAS unsigned char* vb_ = Vb + buf * AV_BUF + vfo;
;             f32x16 p[2];
; #pragma unroll
;             for (int kb = 0; kb < 2; ++kb) {
; #pragma unroll
;                 for (int r = 0; r < 16; ++r) p[kb][r] = 0.f;
; #pragma unroll
;                 for (int ks = 0; ks < 8; ++ks) { const bf16x8 a = *(const LAS bf16x8*)(kb_ + kb * 32 * AK_ROWB + ks * 32); p[kb] = __builtin_amdgcn_mfma_f32_32x32x16_bf16(a, qr[ks], p[kb], 0, 0, 0); }
;             }
;             const bool needmask = (kt * 64 + 63 >= q0 + wid * 32);
;             float T[2];
; #pragma unroll
;     ...
;                 float run = 0.f; const int s0 = kt * 64 + kb * 32 + hi * 16;
; #pragma unroll
;                 for (int r = 15; r >= 0; --r) {
;                     const float z = p[kb][r];
;                     const float e = __builtin_amdgcn_exp2f(z);
;                     float sp = __builtin_amdgcn_logf(1.0f + e);
;                     float a = __builtin_amdgcn_exp2f(z - sp - run);
;                     if (needmask && !(s0 + r < tq)) { sp = 0.f; a = 0.f; }
;                     run += sp; p[kb][r] = a; }
.LBB0_467:
	s_xor_b64 s[16:17], s[16:17], -1
	s_andn2_b64 vcc, exec, s[16:17]
	s_mov_b64 s[16:17], -1
	s_cbranch_vccnz .LBB0_470
	s_add_i32 s3, s18, 64
	s_cmp_ge_i32 s3, s13
	s_mov_b64 s[16:17], 0
	s_cbranch_scc1 .LBB0_470
	s_mul_i32 s3, s26, 0x4400
	v_add_u32_e32 v175, s3, v190
	ds_read_b128 v[64:67], v175
	ds_read_b128 v[80:83], v175 offset:32
	s_add_i32 s3, s18, 0x7f
	s_cmp_lt_i32 s3, s23
	s_cselect_b64 s[62:63], -1, 0
	s_waitcnt lgkmcnt(1)
	v_mfma_f32_32x32x16_bf16 v[64:79], v[64:67], v[106:109], 0
	s_mul_i32 s16, s26, 0x4800
	ds_read_b128 v[194:197], v175 offset:8736
	s_waitcnt lgkmcnt(1)
	v_mfma_f32_32x32x16_bf16 v[64:79], v[80:83], v[110:113], v[64:79]
	ds_read_b128 v[80:83], v175 offset:64
	s_waitcnt lgkmcnt(0)
	v_mfma_f32_32x32x16_bf16 v[64:79], v[80:83], v[118:121], v[64:79]
	ds_read_b128 v[80:83], v175 offset:96
	s_waitcnt lgkmcnt(0)
	v_mfma_f32_32x32x16_bf16 v[64:79], v[80:83], v[122:125], v[64:79]
	ds_read_b128 v[80:83], v175 offset:128
	s_waitcnt lgkmcnt(0)
	v_mfma_f32_32x32x16_bf16 v[64:79], v[80:83], v[126:129], v[64:79]
	ds_read_b128 v[80:83], v175 offset:160
	s_waitcnt lgkmcnt(0)
	v_mfma_f32_32x32x16_bf16 v[64:79], v[80:83], v[134:137], v[64:79]
	ds_read_b128 v[80:83], v175 offset:192
	s_waitcnt lgkmcnt(0)
	v_mfma_f32_32x32x16_bf16 v[64:79], v[80:83], v[138:141], v[64:79]
	ds_read_b128 v[80:83], v175 offset:224
	s_waitcnt lgkmcnt(0)
	v_mfma_f32_32x32x16_bf16 v[64:79], v[80:83], v[142:145], v[64:79]
	ds_read_b128 v[80:83], v175 offset:8704
	s_waitcnt lgkmcnt(0)
	v_mfma_f32_32x32x16_bf16 v[80:95], v[80:83], v[106:109], 0
	v_mfma_f32_32x32x16_bf16 v[80:95], v[194:197], v[110:113], v[80:95]
	ds_read_b128 v[194:197], v175 offset:8768
	s_waitcnt lgkmcnt(0)
	v_mfma_f32_32x32x16_bf16 v[80:95], v[194:197], v[118:121], v[80:95]
	ds_read_b128 v[194:197], v175 offset:8800
	s_waitcnt lgkmcnt(0)
	v_mfma_f32_32x32x16_bf16 v[80:95], v[194:197], v[122:125], v[80:95]
	ds_read_b128 v[194:197], v175 offset:8832
	s_waitcnt lgkmcnt(0)
	v_mfma_f32_32x32x16_bf16 v[80:95], v[194:197], v[126:129], v[80:95]
	ds_read_b128 v[194:197], v175 offset:8864
	s_waitcnt lgkmcnt(0)
	v_mfma_f32_32x32x16_bf16 v[80:95], v[194:197], v[134:137], v[80:95]
	ds_read_b128 v[194:197], v175 offset:8896
	s_waitcnt lgkmcnt(0)
	v_mfma_f32_32x32x16_bf16 v[80:95], v[194:197], v[138:141], v[80:95]
	ds_read_b128 v[194:197], v175 offset:8928
	s_waitcnt lgkmcnt(0)
	v_mfma_f32_32x32x16_bf16 v[80:95], v[194:197], v[142:145], v[80:95]
	v_add_u32_e32 v194, s18, v161
	v_add_u32_e32 v197, 0x6f, v194
	v_cmp_lt_i32_e32 vcc, v197, v173
	s_or_b64 vcc, s[62:63], vcc
	v_add_u32_e32 v198, 0x6e, v194
	v_add_u32_e32 v195, 0x60, v194
	v_add_u32_e32 v175, 64, v194
	s_nop 4
	v_exp_f32_e32 v196, v95
	v_exp_f32_e32 v197, v94
	v_add_f32_e32 v196, 1.0, v196
	v_log_f32_e32 v196, v196
	v_add_f32_e32 v197, 1.0, v197
	v_log_f32_e32 v197, v197
	v_sub_f32_e32 v95, v95, v196
	v_exp_f32_e32 v95, v95
	v_add_f32_e32 v196, 0, v196
	v_cndmask_b32_e32 v196, 0, v196, vcc
	v_sub_f32_e32 v94, v94, v197
	v_cndmask_b32_e32 v95, 0, v95, vcc
	v_cmp_lt_i32_e32 vcc, v198, v173
	s_or_b64 vcc, s[62:63], vcc
	v_sub_f32_e32 v94, v94, v196
	v_cndmask_b32_e32 v197, 0, v197, vcc
	v_add_f32_e32 v196, v197, v196
	v_exp_f32_e32 v197, v93
	v_exp_f32_e32 v94, v94
	v_add_u32_e32 v198, 0x6d, v194
	v_add_f32_e32 v197, 1.0, v197
	v_log_f32_e32 v197, v197
	v_cndmask_b32_e32 v94, 0, v94, vcc
	v_cmp_lt_i32_e32 vcc, v198, v173
	s_or_b64 vcc, s[62:63], vcc
	v_sub_f32_e32 v93, v93, v197
	v_cndmask_b32_e32 v197, 0, v197, vcc
	v_sub_f32_e32 v93, v93, v196
	v_add_f32_e32 v196, v197, v196
	v_exp_f32_e32 v197, v92
	v_exp_f32_e32 v93, v93
	v_add_u32_e32 v198, 0x6c, v194
	v_add_f32_e32 v197, 1.0, v197
	v_log_f32_e32 v197, v197
	v_cndmask_b32_e32 v93, 0, v93, vcc
	v_cmp_lt_i32_e32 vcc, v198, v173
	s_or_b64 vcc, s[62:63], vcc
	v_sub_f32_e32 v92, v92, v197
	v_cndmask_b32_e32 v197, 0, v197, vcc
	v_sub_f32_e32 v92, v92, v196
	v_add_f32_e32 v196, v197, v196
	v_exp_f32_e32 v197, v91
	v_exp_f32_e32 v92, v92
	v_add_u32_e32 v198, 0x6b, v194
	v_add_f32_e32 v197, 1.0, v197
	v_log_f32_e32 v197, v197
	v_cndmask_b32_e32 v92, 0, v92, vcc
	v_cmp_lt_i32_e32 vcc, v198, v173
	s_or_b64 vcc, s[62:63], vcc
	v_sub_f32_e32 v91, v91, v197
	v_cndmask_b32_e32 v197, 0, v197, vcc
	v_sub_f32_e32 v91, v91, v196
	v_add_f32_e32 v196, v197, v196
	v_exp_f32_e32 v197, v90
	v_exp_f32_e32 v91, v91
	v_add_u32_e32 v198, 0x6a, v194
	v_add_f32_e32 v197, 1.0, v197
	v_log_f32_e32 v197, v197
	v_cndmask_b32_e32 v91, 0, v91, vcc
	v_cmp_lt_i32_e32 vcc, v198, v173
	s_or_b64 vcc, s[62:63], vcc
	v_sub_f32_e32 v90, v90, v197
	v_cndmask_b32_e32 v197, 0, v197, vcc
	v_sub_f32_e32 v90, v90, v196
	v_add_f32_e32 v196, v197, v196
	v_exp_f32_e32 v197, v89
	v_exp_f32_e32 v90, v90
	v_add_u32_e32 v198, 0x69, v194
	v_add_f32_e32 v197, 1.0, v197
	v_log_f32_e32 v197, v197
	v_cndmask_b32_e32 v90, 0, v90, vcc
	v_cmp_lt_i32_e32 vcc, v198, v173
	s_or_b64 vcc, s[62:63], vcc
	v_sub_f32_e32 v89, v89, v197
	v_cndmask_b32_e32 v197, 0, v197, vcc
	v_sub_f32_e32 v89, v89, v196
	v_add_f32_e32 v196, v197, v196
	v_exp_f32_e32 v197, v88
	v_exp_f32_e32 v89, v89
	v_add_u32_e32 v198, 0x68, v194
	v_add_f32_e32 v197, 1.0, v197
	v_log_f32_e32 v197, v197
	v_cndmask_b32_e32 v89, 0, v89, vcc
	v_cmp_lt_i32_e32 vcc, v198, v173
	s_or_b64 vcc, s[62:63], vcc
	v_sub_f32_e32 v88, v88, v197
	v_cndmask_b32_e32 v197, 0, v197, vcc
	v_sub_f32_e32 v88, v88, v196
	v_add_f32_e32 v196, v197, v196
	v_exp_f32_e32 v197, v87
	v_exp_f32_e32 v88, v88
	v_add_u32_e32 v198, 0x67, v194
	v_add_f32_e32 v197, 1.0, v197
	v_log_f32_e32 v197, v197
	v_cndmask_b32_e32 v88, 0, v88, vcc
	v_cmp_lt_i32_e32 vcc, v198, v173
	s_or_b64 vcc, s[62:63], vcc
	v_sub_f32_e32 v87, v87, v197
; __device__ __forceinline__ void attn_unit(int b, int h, int qb, const bf16_t* __restrict__ QK, const bf16_t* __restrict__ VT, bf16_t* __restrict__ O, const float* __restrict__ qg, const float* __restrict__ kg, ...
;     ...
;                 float run = 0.f; const int s0 = kt * 64 + kb * 32 + hi * 16;
; #pragma unroll
;                 for (int r = 15; r >= 0; --r) {
;                     const float z = p[kb][r];
;                     const float e = __builtin_amdgcn_exp2f(z);
;                     float sp = __builtin_amdgcn_logf(1.0f + e);
;                     float a = __builtin_amdgcn_exp2f(z - sp - run);
;                     if (needmask && !(s0 + r < tq)) { sp = 0.f; a = 0.f; }
;                     run += sp; p[kb][r] = a; }
;                 T[kb] = run; }
	v_cndmask_b32_e32 v197, 0, v197, vcc
	v_sub_f32_e32 v87, v87, v196
	v_add_f32_e32 v196, v197, v196
	v_exp_f32_e32 v197, v86
	v_exp_f32_e32 v87, v87
	v_add_u32_e32 v198, 0x66, v194
	v_add_f32_e32 v197, 1.0, v197
	v_log_f32_e32 v197, v197
	v_cndmask_b32_e32 v87, 0, v87, vcc
	v_cmp_lt_i32_e32 vcc, v198, v173
	s_or_b64 vcc, s[62:63], vcc
	v_sub_f32_e32 v86, v86, v197
	v_cndmask_b32_e32 v197, 0, v197, vcc
	v_sub_f32_e32 v86, v86, v196
	v_add_f32_e32 v196, v197, v196
	v_exp_f32_e32 v197, v85
	v_exp_f32_e32 v86, v86
	v_add_u32_e32 v198, 0x65, v194
	v_add_f32_e32 v197, 1.0, v197
	v_log_f32_e32 v197, v197
	v_cndmask_b32_e32 v86, 0, v86, vcc
	v_cmp_lt_i32_e32 vcc, v198, v173
	s_or_b64 vcc, s[62:63], vcc
	v_sub_f32_e32 v85, v85, v197
	v_cndmask_b32_e32 v197, 0, v197, vcc
	v_sub_f32_e32 v85, v85, v196
	v_add_f32_e32 v196, v197, v196
	v_exp_f32_e32 v197, v84
	v_exp_f32_e32 v85, v85
	v_add_u32_e32 v198, 0x64, v194
	v_add_f32_e32 v197, 1.0, v197
	v_log_f32_e32 v197, v197
	v_cndmask_b32_e32 v85, 0, v85, vcc
	v_cmp_lt_i32_e32 vcc, v198, v173
	s_or_b64 vcc, s[62:63], vcc
	v_sub_f32_e32 v84, v84, v197
	v_cndmask_b32_e32 v197, 0, v197, vcc
	v_sub_f32_e32 v84, v84, v196
	v_add_f32_e32 v196, v197, v196
	v_exp_f32_e32 v197, v83
	v_exp_f32_e32 v84, v84
	v_add_u32_e32 v198, 0x63, v194
	v_add_f32_e32 v197, 1.0, v197
	v_log_f32_e32 v197, v197
	v_cndmask_b32_e32 v84, 0, v84, vcc
	v_cmp_lt_i32_e32 vcc, v198, v173
	s_or_b64 vcc, s[62:63], vcc
	v_sub_f32_e32 v83, v83, v197
	v_cndmask_b32_e32 v197, 0, v197, vcc
	v_sub_f32_e32 v83, v83, v196
	v_add_f32_e32 v196, v197, v196
	v_exp_f32_e32 v197, v82
	v_exp_f32_e32 v83, v83
	v_add_u32_e32 v198, 0x62, v194
	v_add_f32_e32 v197, 1.0, v197
	v_log_f32_e32 v197, v197
	v_cndmask_b32_e32 v83, 0, v83, vcc
	v_cmp_lt_i32_e32 vcc, v198, v173
	s_or_b64 vcc, s[62:63], vcc
	v_sub_f32_e32 v82, v82, v197
	v_cndmask_b32_e32 v197, 0, v197, vcc
	v_sub_f32_e32 v82, v82, v196
	v_add_f32_e32 v196, v197, v196
	v_exp_f32_e32 v197, v81
	v_exp_f32_e32 v82, v82
	v_add_u32_e32 v198, 0x61, v194
	v_add_f32_e32 v197, 1.0, v197
	v_log_f32_e32 v197, v197
	v_cndmask_b32_e32 v82, 0, v82, vcc
	v_cmp_lt_i32_e32 vcc, v198, v173
	s_or_b64 vcc, s[62:63], vcc
	v_sub_f32_e32 v81, v81, v197
	v_cndmask_b32_e32 v197, 0, v197, vcc
	v_sub_f32_e32 v81, v81, v196
	v_add_f32_e32 v196, v197, v196
	v_exp_f32_e32 v197, v80
	v_exp_f32_e32 v81, v81
	v_add_u32_e32 v198, 0x4e, v194
	v_add_f32_e32 v197, 1.0, v197
	v_log_f32_e32 v197, v197
	v_cndmask_b32_e32 v81, 0, v81, vcc
	v_cmp_lt_i32_e32 vcc, v195, v173
	s_or_b64 vcc, s[62:63], vcc
	v_sub_f32_e32 v80, v80, v197
	v_cndmask_b32_e32 v195, 0, v197, vcc
	v_sub_f32_e32 v80, v80, v196
	v_add_f32_e32 v195, v195, v196
	v_exp_f32_e32 v196, v79
	v_exp_f32_e32 v80, v80
	v_add_u32_e32 v197, 0x4f, v194
	v_add_f32_e32 v196, 1.0, v196
	v_log_f32_e32 v196, v196
	v_cndmask_b32_e32 v80, 0, v80, vcc
	v_cmp_lt_i32_e32 vcc, v197, v173
	v_exp_f32_e32 v197, v78
	v_sub_f32_e32 v79, v79, v196
	v_exp_f32_e32 v79, v79
	s_or_b64 vcc, s[62:63], vcc
	v_add_f32_e32 v197, 1.0, v197
	v_log_f32_e32 v197, v197
	v_add_f32_e32 v196, 0, v196
	v_cndmask_b32_e32 v79, 0, v79, vcc
	v_cndmask_b32_e32 v196, 0, v196, vcc
	v_cmp_lt_i32_e32 vcc, v198, v173
	s_or_b64 vcc, s[62:63], vcc
	v_sub_f32_e32 v78, v78, v197
	v_cndmask_b32_e32 v197, 0, v197, vcc
	v_sub_f32_e32 v78, v78, v196
	v_add_f32_e32 v196, v197, v196
	v_exp_f32_e32 v197, v77
	v_exp_f32_e32 v78, v78
	v_add_u32_e32 v198, 0x4d, v194
	v_add_f32_e32 v197, 1.0, v197
	v_log_f32_e32 v197, v197
	v_cndmask_b32_e32 v78, 0, v78, vcc
	v_cmp_lt_i32_e32 vcc, v198, v173
	s_or_b64 vcc, s[62:63], vcc
	v_sub_f32_e32 v77, v77, v197
	v_cndmask_b32_e32 v197, 0, v197, vcc
	v_sub_f32_e32 v77, v77, v196
	v_add_f32_e32 v196, v197, v196
	v_exp_f32_e32 v197, v76
	v_exp_f32_e32 v77, v77
	v_add_u32_e32 v198, 0x4c, v194
	v_add_f32_e32 v197, 1.0, v197
	v_log_f32_e32 v197, v197
	v_cndmask_b32_e32 v77, 0, v77, vcc
	v_cmp_lt_i32_e32 vcc, v198, v173
	s_or_b64 vcc, s[62:63], vcc
	v_sub_f32_e32 v76, v76, v197
	v_cndmask_b32_e32 v197, 0, v197, vcc
	v_sub_f32_e32 v76, v76, v196
	v_add_f32_e32 v196, v197, v196
	v_exp_f32_e32 v197, v75
	v_exp_f32_e32 v76, v76
	v_add_u32_e32 v198, 0x4b, v194
	v_add_f32_e32 v197, 1.0, v197
	v_log_f32_e32 v197, v197
	v_cndmask_b32_e32 v76, 0, v76, vcc
	v_cmp_lt_i32_e32 vcc, v198, v173
	s_or_b64 vcc, s[62:63], vcc
	v_sub_f32_e32 v75, v75, v197
	v_cndmask_b32_e32 v197, 0, v197, vcc
	v_sub_f32_e32 v75, v75, v196
	v_add_f32_e32 v196, v197, v196
	v_exp_f32_e32 v197, v74
	v_exp_f32_e32 v75, v75
	v_add_u32_e32 v198, 0x4a, v194
	v_add_f32_e32 v197, 1.0, v197
	v_log_f32_e32 v197, v197
	v_cndmask_b32_e32 v75, 0, v75, vcc
	v_cmp_lt_i32_e32 vcc, v198, v173
	s_or_b64 vcc, s[62:63], vcc
	v_sub_f32_e32 v74, v74, v197
	v_cndmask_b32_e32 v197, 0, v197, vcc
	v_sub_f32_e32 v74, v74, v196
	v_add_f32_e32 v196, v197, v196
	v_exp_f32_e32 v197, v73
	v_exp_f32_e32 v74, v74
	v_add_u32_e32 v198, 0x49, v194
	v_add_f32_e32 v197, 1.0, v197
	v_log_f32_e32 v197, v197
	v_cndmask_b32_e32 v74, 0, v74, vcc
	v_cmp_lt_i32_e32 vcc, v198, v173
	s_or_b64 vcc, s[62:63], vcc
	v_sub_f32_e32 v73, v73, v197
	v_cndmask_b32_e32 v197, 0, v197, vcc
	v_sub_f32_e32 v73, v73, v196
	v_add_f32_e32 v196, v197, v196
	v_exp_f32_e32 v197, v72
	v_exp_f32_e32 v73, v73
	v_add_u32_e32 v198, 0x48, v194
	v_add_f32_e32 v197, 1.0, v197
	v_log_f32_e32 v197, v197
	v_cndmask_b32_e32 v73, 0, v73, vcc
	v_cmp_lt_i32_e32 vcc, v198, v173
	s_or_b64 vcc, s[62:63], vcc
	v_sub_f32_e32 v72, v72, v197
	v_cndmask_b32_e32 v197, 0, v197, vcc
	v_sub_f32_e32 v72, v72, v196
	v_add_f32_e32 v196, v197, v196
	v_exp_f32_e32 v197, v71
	v_exp_f32_e32 v72, v72
	v_add_u32_e32 v198, 0x47, v194
	v_add_f32_e32 v197, 1.0, v197
; #define LAS __attribute__((address_space(3)))
; __device__ __forceinline__ unsigned pk2(float lo, float hi) { f32x2 v = {lo, hi}; bf16x2_t b = __builtin_convertvector(v, bf16x2_t); return __builtin_bit_cast(unsigned, b); }
; __device__ __forceinline__ void attn_unit(int b, int h, int qb, const bf16_t* __restrict__ QK, const bf16_t* __restrict__ VT, bf16_t* __restrict__ O, const float* __restrict__ qg, const float* __restrict__ kg, ...
;     ...
;                 float run = 0.f; const int s0 = kt * 64 + kb * 32 + hi * 16;
; #pragma unroll
;                 for (int r = 15; r >= 0; --r) {
;                     const float z = p[kb][r];
;                     const float e = __builtin_amdgcn_exp2f(z);
;                     float sp = __builtin_amdgcn_logf(1.0f + e);
;                     float a = __builtin_amdgcn_exp2f(z - sp - run);
;                     if (needmask && !(s0 + r < tq)) { sp = 0.f; a = 0.f; }
;                     run += sp; p[kb][r] = a; }
;                 T[kb] = run; }
;             const float T0o = __shfl_xor(T[0], 32), T1o = __shfl_xor(T[1], 32);
;             const float base1 = R + (hi == 0 ? T1o : 0.f), base0 = R + T[1] + T1o + (hi == 0 ? T0o : 0.f);
;             const float f0 = __builtin_amdgcn_exp2f(-base0), f1 = __builtin_amdgcn_exp2f(-base1);
;             R += (T[0] + T0o) + (T[1] + T1o);
;             bf16x8 pa[2][2];
; #pragma unroll
;             for (int kb = 0; kb < 2; ++kb) { const float f = kb ? f1 : f0;
; #pragma unroll
;                 for (int s2 = 0; s2 < 2; ++s2) { u32x4 w;
;                     w.x = pk2(p[kb][8 * s2 + 0] * f, p[kb][8 * s2 + 1] * f); w.y = pk2(p[kb][8 * s2 + 2] * f, p[kb][8 * s2 + 3] * f);
;                     w.z = pk2(p[kb][8 * s2 + 4] * f, p[kb][8 * s2 + 5] * f); w.w = pk2(p[kb][8 * s2 + 6] * f, p[kb][8 * s2 + 7] * f);
;                     pa[kb][s2] = __builtin_bit_cast(bf16x8, w); } }
; #pragma unroll
;             for (int d = 0; d < 4; ++d)
; #pragma unroll
;                 for (int kb = 0; kb < 2; ++kb)
; #pragma unroll
;                     for (int s2 = 0; s2 < 2; ++s2) { const bf16x8 vb = *(const LAS bf16x8*)(vb_ + d * 32 * AV_ROWB + kb * 64 + s2 * 16); o[d] = __builtin_amdgcn_mfma_f32_32x32x16_bf16(pa[kb][s2], vb, o[d], 0, 0, 0); }
;             wdone = __all(R >= ATT_DONE_LOG2) != 0;
	v_log_f32_e32 v197, v197
	v_cndmask_b32_e32 v72, 0, v72, vcc
	v_cmp_lt_i32_e32 vcc, v198, v173
	s_or_b64 vcc, s[62:63], vcc
	v_sub_f32_e32 v71, v71, v197
	v_cndmask_b32_e32 v197, 0, v197, vcc
	v_sub_f32_e32 v71, v71, v196
	v_add_f32_e32 v196, v197, v196
	v_exp_f32_e32 v197, v70
	v_exp_f32_e32 v71, v71
	v_add_u32_e32 v198, 0x46, v194
	v_add_f32_e32 v197, 1.0, v197
	v_log_f32_e32 v197, v197
	v_cndmask_b32_e32 v71, 0, v71, vcc
	v_cmp_lt_i32_e32 vcc, v198, v173
	s_or_b64 vcc, s[62:63], vcc
	v_sub_f32_e32 v70, v70, v197
	v_cndmask_b32_e32 v197, 0, v197, vcc
	v_sub_f32_e32 v70, v70, v196
	v_add_f32_e32 v196, v197, v196
	v_exp_f32_e32 v197, v69
	v_exp_f32_e32 v70, v70
	v_add_u32_e32 v198, 0x45, v194
	v_add_f32_e32 v197, 1.0, v197
	v_log_f32_e32 v197, v197
	v_cndmask_b32_e32 v70, 0, v70, vcc
	v_cmp_lt_i32_e32 vcc, v198, v173
	s_or_b64 vcc, s[62:63], vcc
	v_sub_f32_e32 v69, v69, v197
	v_cndmask_b32_e32 v197, 0, v197, vcc
	v_sub_f32_e32 v69, v69, v196
	v_add_f32_e32 v196, v197, v196
	v_exp_f32_e32 v197, v68
	v_exp_f32_e32 v69, v69
	v_add_u32_e32 v198, 0x44, v194
	v_add_f32_e32 v197, 1.0, v197
	v_log_f32_e32 v197, v197
	v_cndmask_b32_e32 v69, 0, v69, vcc
	v_cmp_lt_i32_e32 vcc, v198, v173
	s_or_b64 vcc, s[62:63], vcc
	v_sub_f32_e32 v68, v68, v197
	v_cndmask_b32_e32 v197, 0, v197, vcc
	v_sub_f32_e32 v68, v68, v196
	v_add_f32_e32 v196, v197, v196
	v_exp_f32_e32 v197, v67
	v_exp_f32_e32 v68, v68
	v_add_u32_e32 v198, 0x43, v194
	v_add_f32_e32 v197, 1.0, v197
	v_log_f32_e32 v197, v197
	v_cndmask_b32_e32 v68, 0, v68, vcc
	v_cmp_lt_i32_e32 vcc, v198, v173
	s_or_b64 vcc, s[62:63], vcc
	v_sub_f32_e32 v67, v67, v197
	v_cndmask_b32_e32 v197, 0, v197, vcc
	v_sub_f32_e32 v67, v67, v196
	v_add_f32_e32 v196, v197, v196
	v_exp_f32_e32 v197, v66
	v_exp_f32_e32 v67, v67
	v_add_u32_e32 v198, 0x42, v194
	v_add_u32_e32 v194, 0x41, v194
	v_add_f32_e32 v197, 1.0, v197
	v_log_f32_e32 v197, v197
	v_cndmask_b32_e32 v67, 0, v67, vcc
	v_cmp_lt_i32_e32 vcc, v198, v173
	s_or_b64 vcc, s[62:63], vcc
	v_sub_f32_e32 v66, v66, v197
	v_cndmask_b32_e32 v197, 0, v197, vcc
	v_sub_f32_e32 v66, v66, v196
	v_add_f32_e32 v196, v197, v196
	v_exp_f32_e32 v197, v65
	v_exp_f32_e32 v66, v66
	v_add_f32_e32 v198, v169, v195
	v_add_f32_e32 v197, 1.0, v197
	v_log_f32_e32 v197, v197
	v_cndmask_b32_e32 v66, 0, v66, vcc
	v_cmp_lt_i32_e32 vcc, v194, v173
	s_or_b64 vcc, s[62:63], vcc
	v_sub_f32_e32 v65, v65, v197
	v_cndmask_b32_e32 v194, 0, v197, vcc
	v_sub_f32_e32 v65, v65, v196
	v_add_f32_e32 v194, v194, v196
	v_exp_f32_e32 v196, v64
	v_exp_f32_e32 v65, v65
	v_add_f32_e32 v196, 1.0, v196
	v_log_f32_e32 v196, v196
	v_cndmask_b32_e32 v65, 0, v65, vcc
	v_cmp_lt_i32_e32 vcc, v175, v173
	s_or_b64 vcc, s[62:63], vcc
	v_sub_f32_e32 v64, v64, v196
	v_cndmask_b32_e32 v175, 0, v196, vcc
	v_add_f32_e32 v175, v175, v194
	v_sub_f32_e32 v64, v64, v194
	ds_bpermute_b32 v194, v157, v175
	ds_bpermute_b32 v196, v157, v195
	v_exp_f32_e32 v64, v64
	s_waitcnt lgkmcnt(1)
	v_cndmask_b32_e64 v199, 0, v194, s[4:5]
	s_waitcnt lgkmcnt(0)
	v_add_f32_e32 v198, v198, v196
	v_add_f32_e32 v198, v199, v198
	v_exp_f32_e64 v198, -v198
	v_cndmask_b32_e32 v64, 0, v64, vcc
	v_cndmask_b32_e64 v197, 0, v196, s[4:5]
	v_add_f32_e32 v197, v169, v197
	v_mul_f32_e32 v64, v64, v198
	v_mul_f32_e32 v65, v65, v198
	v_cvt_pk_bf16_f32 v64, v64, v65
	v_mul_f32_e32 v65, v66, v198
	v_mul_f32_e32 v66, v67, v198
	v_cvt_pk_bf16_f32 v65, v65, v66
	v_mul_f32_e32 v66, v68, v198
	v_mul_f32_e32 v67, v69, v198
	v_cvt_pk_bf16_f32 v66, v66, v67
	v_mul_f32_e32 v67, v70, v198
	v_mul_f32_e32 v68, v71, v198
	v_exp_f32_e64 v197, -v197
	v_cvt_pk_bf16_f32 v67, v67, v68
	v_mul_f32_e32 v68, v72, v198
	v_mul_f32_e32 v69, v73, v198
	v_cvt_pk_bf16_f32 v68, v68, v69
	v_mul_f32_e32 v69, v74, v198
	v_mul_f32_e32 v70, v75, v198
	v_cvt_pk_bf16_f32 v69, v69, v70
	v_mul_f32_e32 v70, v76, v198
	v_mul_f32_e32 v71, v77, v198
	v_cvt_pk_bf16_f32 v70, v70, v71
	v_mul_f32_e32 v71, v78, v198
	v_mul_f32_e32 v72, v79, v198
	v_cvt_pk_bf16_f32 v71, v71, v72
	v_mul_f32_e32 v72, v197, v80
	v_mul_f32_e32 v73, v197, v81
	v_cvt_pk_bf16_f32 v76, v72, v73
	v_mul_f32_e32 v72, v197, v82
	v_mul_f32_e32 v73, v197, v83
	v_cvt_pk_bf16_f32 v77, v72, v73
	v_mul_f32_e32 v72, v197, v84
	v_mul_f32_e32 v73, v197, v85
	v_cvt_pk_bf16_f32 v78, v72, v73
	v_mul_f32_e32 v72, v197, v86
	v_mul_f32_e32 v73, v197, v87
	v_cvt_pk_bf16_f32 v79, v72, v73
	v_mul_f32_e32 v72, v197, v88
	v_mul_f32_e32 v73, v197, v89
	v_cvt_pk_bf16_f32 v72, v72, v73
	v_mul_f32_e32 v73, v197, v90
	v_mul_f32_e32 v74, v197, v91
	v_cvt_pk_bf16_f32 v73, v73, v74
	v_mul_f32_e32 v74, v197, v92
	v_mul_f32_e32 v75, v197, v93
	v_cvt_pk_bf16_f32 v74, v74, v75
	v_mul_f32_e32 v75, v197, v94
	v_mul_f32_e32 v80, v197, v95
	v_add_u32_e32 v88, s16, v191
	v_cvt_pk_bf16_f32 v75, v75, v80
	ds_read_b128 v[80:83], v88 offset:34816
	ds_read_b128 v[84:87], v88 offset:34832
	ds_read_b128 v[92:95], v88 offset:34880
	s_waitcnt lgkmcnt(2)
	v_mfma_f32_32x32x16_bf16 v[0:15], v[64:67], v[80:83], v[0:15]
	ds_read_b128 v[80:83], v88 offset:34896
	v_add_f32_e32 v175, v175, v194
	v_add_f32_e32 v194, v195, v196
	v_add_f32_e32 v175, v175, v194
	v_add_f32_e32 v169, v169, v175
	v_cmp_le_f32_e32 vcc, s72, v169
	s_cmp_eq_u64 vcc, exec
	s_waitcnt lgkmcnt(2)
	v_mfma_f32_32x32x16_bf16 v[0:15], v[68:71], v[84:87], v[0:15]
	ds_read_b128 v[84:87], v88 offset:39424
	s_cselect_b64 s[16:17], -1, 0
	s_waitcnt lgkmcnt(2)
	v_mfma_f32_32x32x16_bf16 v[0:15], v[76:79], v[92:95], v[0:15]
	ds_read_b128 v[92:95], v88 offset:39440
	s_waitcnt lgkmcnt(2)
	v_mfma_f32_32x32x16_bf16 v[0:15], v[72:75], v[80:83], v[0:15]
	ds_read_b128 v[80:83], v88 offset:39488
	s_waitcnt lgkmcnt(2)
	v_mfma_f32_32x32x16_bf16 v[48:63], v[64:67], v[84:87], v[48:63]
	ds_read_b128 v[84:87], v88 offset:39504
	s_waitcnt lgkmcnt(2)
	v_mfma_f32_32x32x16_bf16 v[48:63], v[68:71], v[92:95], v[48:63]
	ds_read_b128 v[92:95], v88 offset:44032
	s_waitcnt lgkmcnt(2)
	v_mfma_f32_32x32x16_bf16 v[48:63], v[76:79], v[80:83], v[48:63]
	ds_read_b128 v[80:83], v88 offset:44048
	s_waitcnt lgkmcnt(2)
	v_mfma_f32_32x32x16_bf16 v[48:63], v[72:75], v[84:87], v[48:63]
	ds_read_b128 v[84:87], v88 offset:44096
	s_waitcnt lgkmcnt(2)
	v_mfma_f32_32x32x16_bf16 v[32:47], v[64:67], v[92:95], v[32:47]
	ds_read_b128 v[92:95], v88 offset:44112
	s_waitcnt lgkmcnt(2)
	v_mfma_f32_32x32x16_bf16 v[32:47], v[68:71], v[80:83], v[32:47]
	ds_read_b128 v[80:83], v88 offset:48640
	s_waitcnt lgkmcnt(2)
	v_mfma_f32_32x32x16_bf16 v[32:47], v[76:79], v[84:87], v[32:47]
	ds_read_b128 v[84:87], v88 offset:48656
	s_waitcnt lgkmcnt(2)
	v_mfma_f32_32x32x16_bf16 v[32:47], v[72:75], v[92:95], v[32:47]
	ds_read_b128 v[92:95], v88 offset:48704
	s_waitcnt lgkmcnt(2)
	v_mfma_f32_32x32x16_bf16 v[16:31], v[64:67], v[80:83], v[16:31]
	ds_read_b128 v[80:83], v88 offset:48720
	s_waitcnt lgkmcnt(2)
	v_mfma_f32_32x32x16_bf16 v[16:31], v[68:71], v[84:87], v[16:31]
	s_waitcnt lgkmcnt(1)
	v_mfma_f32_32x32x16_bf16 v[16:31], v[76:79], v[92:95], v[16:31]
	s_waitcnt lgkmcnt(0)
	v_mfma_f32_32x32x16_bf16 v[16:31], v[72:75], v[80:83], v[16:31]

; #define LAS __attribute__((address_space(3)))
; __device__ __forceinline__ void attn_unit(int b, int h, int qb, const bf16_t* __restrict__ QK, const bf16_t* __restrict__ VT, bf16_t* __restrict__ O, const float* __restrict__ qg, const float* __restrict__ kg, ...
;     ...
;         if (!wdone && kt * 64 < q0 + wid * 32 + 31) {
;             const LAS unsigned char* kb_ = Kb + buf * AK_BUF + kfo; const LAS unsigned char* vb_ = Vb + buf * AV_BUF + vfo;
;             f32x16 p[2];
; #pragma unroll
;             for (int kb = 0; kb < 2; ++kb) {
; #pragma unroll
;                 for (int r = 0; r < 16; ++r) p[kb][r] = 0.f;
; #pragma unroll
;                 for (int ks = 0; ks < 8; ++ks) { const bf16x8 a = *(const LAS bf16x8*)(kb_ + kb * 32 * AK_ROWB + ks * 32); p[kb] = __builtin_amdgcn_mfma_f32_32x32x16_bf16(a, qr[ks], p[kb], 0, 0, 0); }
;             }
;             const bool needmask = (kt * 64 + 63 >= q0 + wid * 32);
;             float T[2];
; #pragma unroll
;     ...
;                 float run = 0.f; const int s0 = kt * 64 + kb * 32 + hi * 16;
; #pragma unroll
;                 for (int r = 15; r >= 0; --r) {
;                     const float z = p[kb][r];
;                     const float e = __builtin_amdgcn_exp2f(z);
;                     float sp = __builtin_amdgcn_logf(1.0f + e);
;                     float a = __builtin_amdgcn_exp2f(z - sp - run);
;                     if (needmask && !(s0 + r < tq)) { sp = 0.f; a = 0.f; }
;                     run += sp; p[kb][r] = a; }
.LBB0_481:
	s_xor_b64 s[16:17], s[16:17], -1
	s_andn2_b64 vcc, exec, s[16:17]
	s_mov_b64 s[16:17], -1
	s_cbranch_vccnz .LBB0_484
	s_add_i32 s3, s18, 64
	s_cmp_ge_i32 s3, s2
	s_mov_b64 s[16:17], 0
	s_cbranch_scc1 .LBB0_484
	s_mul_i32 s3, s24, 0x4400
	v_add_u32_e32 v171, s3, v190
	ds_read_b128 v[64:67], v171
	ds_read_b128 v[80:83], v171 offset:32
	v_add_u32_e32 v175, s18, v161
	s_add_i32 s3, s18, 0x7f
	s_cmp_lt_i32 s3, s23
	s_waitcnt lgkmcnt(1)
	v_mfma_f32_32x32x16_bf16 v[64:79], v[64:67], v[106:109], 0
	s_cselect_b64 s[62:63], -1, 0
	v_add_u32_e32 v184, 0x60, v175
	s_mul_i32 s16, s24, 0x4800
	ds_read_b128 v[192:195], v171 offset:8736
	s_waitcnt lgkmcnt(1)
	v_mfma_f32_32x32x16_bf16 v[64:79], v[80:83], v[110:113], v[64:79]
	ds_read_b128 v[80:83], v171 offset:64
	s_waitcnt lgkmcnt(0)
	v_mfma_f32_32x32x16_bf16 v[64:79], v[80:83], v[118:121], v[64:79]
	ds_read_b128 v[80:83], v171 offset:96
	s_waitcnt lgkmcnt(0)
	v_mfma_f32_32x32x16_bf16 v[64:79], v[80:83], v[122:125], v[64:79]
	ds_read_b128 v[80:83], v171 offset:128
	s_waitcnt lgkmcnt(0)
	v_mfma_f32_32x32x16_bf16 v[64:79], v[80:83], v[126:129], v[64:79]
	ds_read_b128 v[80:83], v171 offset:160
	s_waitcnt lgkmcnt(0)
	v_mfma_f32_32x32x16_bf16 v[64:79], v[80:83], v[134:137], v[64:79]
	ds_read_b128 v[80:83], v171 offset:192
	s_waitcnt lgkmcnt(0)
	v_mfma_f32_32x32x16_bf16 v[64:79], v[80:83], v[138:141], v[64:79]
	ds_read_b128 v[80:83], v171 offset:224
	s_waitcnt lgkmcnt(0)
	v_mfma_f32_32x32x16_bf16 v[64:79], v[80:83], v[142:145], v[64:79]
	ds_read_b128 v[80:83], v171 offset:8704
	s_waitcnt lgkmcnt(0)
	v_mfma_f32_32x32x16_bf16 v[80:95], v[80:83], v[106:109], 0
	v_mfma_f32_32x32x16_bf16 v[80:95], v[192:195], v[110:113], v[80:95]
	ds_read_b128 v[192:195], v171 offset:8768
	s_waitcnt lgkmcnt(0)
	v_mfma_f32_32x32x16_bf16 v[80:95], v[192:195], v[118:121], v[80:95]
	ds_read_b128 v[192:195], v171 offset:8800
	s_waitcnt lgkmcnt(0)
	v_mfma_f32_32x32x16_bf16 v[80:95], v[192:195], v[122:125], v[80:95]
	ds_read_b128 v[192:195], v171 offset:8832
	s_waitcnt lgkmcnt(0)
	v_mfma_f32_32x32x16_bf16 v[80:95], v[192:195], v[126:129], v[80:95]
	ds_read_b128 v[192:195], v171 offset:8864
	s_waitcnt lgkmcnt(0)
	v_mfma_f32_32x32x16_bf16 v[80:95], v[192:195], v[134:137], v[80:95]
	ds_read_b128 v[192:195], v171 offset:8896
	s_waitcnt lgkmcnt(0)
	v_mfma_f32_32x32x16_bf16 v[80:95], v[192:195], v[138:141], v[80:95]
	ds_read_b128 v[192:195], v171 offset:8928
	v_add_u32_e32 v171, 64, v175
	s_waitcnt lgkmcnt(0)
	v_mfma_f32_32x32x16_bf16 v[80:95], v[192:195], v[142:145], v[80:95]
	v_add_u32_e32 v193, 0x6f, v175
	v_cmp_lt_i32_e32 vcc, v193, v173
	s_or_b64 vcc, s[62:63], vcc
	v_add_u32_e32 v194, 0x6e, v175
	s_nop 7
	v_exp_f32_e32 v192, v95
	v_exp_f32_e32 v193, v94
	v_add_f32_e32 v192, 1.0, v192
	v_log_f32_e32 v192, v192
	v_add_f32_e32 v193, 1.0, v193
	v_log_f32_e32 v193, v193
	v_sub_f32_e32 v95, v95, v192
	v_exp_f32_e32 v95, v95
	v_add_f32_e32 v192, 0, v192
	v_cndmask_b32_e32 v192, 0, v192, vcc
	v_sub_f32_e32 v94, v94, v193
	v_cndmask_b32_e32 v95, 0, v95, vcc
	v_cmp_lt_i32_e32 vcc, v194, v173
	s_or_b64 vcc, s[62:63], vcc
	v_sub_f32_e32 v94, v94, v192
	v_cndmask_b32_e32 v193, 0, v193, vcc
	v_add_f32_e32 v192, v193, v192
	v_exp_f32_e32 v193, v93
	v_exp_f32_e32 v94, v94
	v_add_u32_e32 v194, 0x6d, v175
	v_add_f32_e32 v193, 1.0, v193
	v_log_f32_e32 v193, v193
	v_cndmask_b32_e32 v94, 0, v94, vcc
	v_cmp_lt_i32_e32 vcc, v194, v173
	s_or_b64 vcc, s[62:63], vcc
	v_sub_f32_e32 v93, v93, v193
	v_cndmask_b32_e32 v193, 0, v193, vcc
	v_sub_f32_e32 v93, v93, v192
	v_add_f32_e32 v192, v193, v192
	v_exp_f32_e32 v193, v92
	v_exp_f32_e32 v93, v93
	v_add_u32_e32 v194, 0x6c, v175
	v_add_f32_e32 v193, 1.0, v193
	v_log_f32_e32 v193, v193
	v_cndmask_b32_e32 v93, 0, v93, vcc
	v_cmp_lt_i32_e32 vcc, v194, v173
	s_or_b64 vcc, s[62:63], vcc
	v_sub_f32_e32 v92, v92, v193
	v_cndmask_b32_e32 v193, 0, v193, vcc
	v_sub_f32_e32 v92, v92, v192
	v_add_f32_e32 v192, v193, v192
	v_exp_f32_e32 v193, v91
	v_exp_f32_e32 v92, v92
	v_add_u32_e32 v194, 0x6b, v175
	v_add_f32_e32 v193, 1.0, v193
	v_log_f32_e32 v193, v193
	v_cndmask_b32_e32 v92, 0, v92, vcc
	v_cmp_lt_i32_e32 vcc, v194, v173
	s_or_b64 vcc, s[62:63], vcc
	v_sub_f32_e32 v91, v91, v193
	v_cndmask_b32_e32 v193, 0, v193, vcc
	v_sub_f32_e32 v91, v91, v192
	v_add_f32_e32 v192, v193, v192
	v_exp_f32_e32 v193, v90
	v_exp_f32_e32 v91, v91
	v_add_u32_e32 v194, 0x6a, v175
	v_add_f32_e32 v193, 1.0, v193
	v_log_f32_e32 v193, v193
	v_cndmask_b32_e32 v91, 0, v91, vcc
	v_cmp_lt_i32_e32 vcc, v194, v173
	s_or_b64 vcc, s[62:63], vcc
	v_sub_f32_e32 v90, v90, v193
	v_cndmask_b32_e32 v193, 0, v193, vcc
	v_sub_f32_e32 v90, v90, v192
	v_add_f32_e32 v192, v193, v192
	v_exp_f32_e32 v193, v89
	v_exp_f32_e32 v90, v90
	v_add_u32_e32 v194, 0x69, v175
	v_add_f32_e32 v193, 1.0, v193
	v_log_f32_e32 v193, v193
	v_cndmask_b32_e32 v90, 0, v90, vcc
	v_cmp_lt_i32_e32 vcc, v194, v173
	s_or_b64 vcc, s[62:63], vcc
	v_sub_f32_e32 v89, v89, v193
	v_cndmask_b32_e32 v193, 0, v193, vcc
	v_sub_f32_e32 v89, v89, v192
	v_add_f32_e32 v192, v193, v192
	v_exp_f32_e32 v193, v88
	v_exp_f32_e32 v89, v89
	v_add_u32_e32 v194, 0x68, v175
	v_add_f32_e32 v193, 1.0, v193
	v_log_f32_e32 v193, v193
	v_cndmask_b32_e32 v89, 0, v89, vcc
	v_cmp_lt_i32_e32 vcc, v194, v173
	s_or_b64 vcc, s[62:63], vcc
	v_sub_f32_e32 v88, v88, v193
	v_cndmask_b32_e32 v193, 0, v193, vcc
	v_sub_f32_e32 v88, v88, v192
	v_add_f32_e32 v192, v193, v192
	v_exp_f32_e32 v193, v87
	v_exp_f32_e32 v88, v88
	v_add_u32_e32 v194, 0x67, v175
	v_add_f32_e32 v193, 1.0, v193
	v_log_f32_e32 v193, v193
	v_cndmask_b32_e32 v88, 0, v88, vcc
	v_cmp_lt_i32_e32 vcc, v194, v173
	s_or_b64 vcc, s[62:63], vcc
	v_sub_f32_e32 v87, v87, v193
; __device__ __forceinline__ void attn_unit(int b, int h, int qb, const bf16_t* __restrict__ QK, const bf16_t* __restrict__ VT, bf16_t* __restrict__ O, const float* __restrict__ qg, const float* __restrict__ kg, ...
;     ...
;                 float run = 0.f; const int s0 = kt * 64 + kb * 32 + hi * 16;
; #pragma unroll
;                 for (int r = 15; r >= 0; --r) {
;                     const float z = p[kb][r];
;                     const float e = __builtin_amdgcn_exp2f(z);
;                     float sp = __builtin_amdgcn_logf(1.0f + e);
;                     float a = __builtin_amdgcn_exp2f(z - sp - run);
;                     if (needmask && !(s0 + r < tq)) { sp = 0.f; a = 0.f; }
;                     run += sp; p[kb][r] = a; }
;                 T[kb] = run; }
	v_cndmask_b32_e32 v193, 0, v193, vcc
	v_sub_f32_e32 v87, v87, v192
	v_add_f32_e32 v192, v193, v192
	v_exp_f32_e32 v193, v86
	v_exp_f32_e32 v87, v87
	v_add_u32_e32 v194, 0x66, v175
	v_add_f32_e32 v193, 1.0, v193
	v_log_f32_e32 v193, v193
	v_cndmask_b32_e32 v87, 0, v87, vcc
	v_cmp_lt_i32_e32 vcc, v194, v173
	s_or_b64 vcc, s[62:63], vcc
	v_sub_f32_e32 v86, v86, v193
	v_cndmask_b32_e32 v193, 0, v193, vcc
	v_sub_f32_e32 v86, v86, v192
	v_add_f32_e32 v192, v193, v192
	v_exp_f32_e32 v193, v85
	v_exp_f32_e32 v86, v86
	v_add_u32_e32 v194, 0x65, v175
	v_add_f32_e32 v193, 1.0, v193
	v_log_f32_e32 v193, v193
	v_cndmask_b32_e32 v86, 0, v86, vcc
	v_cmp_lt_i32_e32 vcc, v194, v173
	s_or_b64 vcc, s[62:63], vcc
	v_sub_f32_e32 v85, v85, v193
	v_cndmask_b32_e32 v193, 0, v193, vcc
	v_sub_f32_e32 v85, v85, v192
	v_add_f32_e32 v192, v193, v192
	v_exp_f32_e32 v193, v84
	v_exp_f32_e32 v85, v85
	v_add_u32_e32 v194, 0x64, v175
	v_add_f32_e32 v193, 1.0, v193
	v_log_f32_e32 v193, v193
	v_cndmask_b32_e32 v85, 0, v85, vcc
	v_cmp_lt_i32_e32 vcc, v194, v173
	s_or_b64 vcc, s[62:63], vcc
	v_sub_f32_e32 v84, v84, v193
	v_cndmask_b32_e32 v193, 0, v193, vcc
	v_sub_f32_e32 v84, v84, v192
	v_add_f32_e32 v192, v193, v192
	v_exp_f32_e32 v193, v83
	v_exp_f32_e32 v84, v84
	v_add_u32_e32 v194, 0x63, v175
	v_add_f32_e32 v193, 1.0, v193
	v_log_f32_e32 v193, v193
	v_cndmask_b32_e32 v84, 0, v84, vcc
	v_cmp_lt_i32_e32 vcc, v194, v173
	s_or_b64 vcc, s[62:63], vcc
	v_sub_f32_e32 v83, v83, v193
	v_cndmask_b32_e32 v193, 0, v193, vcc
	v_sub_f32_e32 v83, v83, v192
	v_add_f32_e32 v192, v193, v192
	v_exp_f32_e32 v193, v82
	v_exp_f32_e32 v83, v83
	v_add_u32_e32 v194, 0x62, v175
	v_add_f32_e32 v193, 1.0, v193
	v_log_f32_e32 v193, v193
	v_cndmask_b32_e32 v83, 0, v83, vcc
	v_cmp_lt_i32_e32 vcc, v194, v173
	s_or_b64 vcc, s[62:63], vcc
	v_sub_f32_e32 v82, v82, v193
	v_cndmask_b32_e32 v193, 0, v193, vcc
	v_sub_f32_e32 v82, v82, v192
	v_add_f32_e32 v192, v193, v192
	v_exp_f32_e32 v193, v81
	v_exp_f32_e32 v82, v82
	v_add_u32_e32 v194, 0x61, v175
	v_add_f32_e32 v193, 1.0, v193
	v_log_f32_e32 v193, v193
	v_cndmask_b32_e32 v82, 0, v82, vcc
	v_cmp_lt_i32_e32 vcc, v194, v173
	s_or_b64 vcc, s[62:63], vcc
	v_sub_f32_e32 v81, v81, v193
	v_cndmask_b32_e32 v193, 0, v193, vcc
	v_sub_f32_e32 v81, v81, v192
	v_add_f32_e32 v192, v193, v192
	v_exp_f32_e32 v193, v80
	v_exp_f32_e32 v81, v81
	v_add_u32_e32 v194, 0x4e, v175
	v_add_f32_e32 v193, 1.0, v193
	v_log_f32_e32 v193, v193
	v_cndmask_b32_e32 v81, 0, v81, vcc
	v_cmp_lt_i32_e32 vcc, v184, v173
	s_or_b64 vcc, s[62:63], vcc
	v_sub_f32_e32 v80, v80, v193
	v_cndmask_b32_e32 v184, 0, v193, vcc
	v_sub_f32_e32 v80, v80, v192
	v_add_f32_e32 v184, v184, v192
	v_exp_f32_e32 v192, v79
	v_exp_f32_e32 v80, v80
	v_add_u32_e32 v193, 0x4f, v175
	v_add_f32_e32 v192, 1.0, v192
	v_log_f32_e32 v192, v192
	v_cndmask_b32_e32 v80, 0, v80, vcc
	v_cmp_lt_i32_e32 vcc, v193, v173
	v_exp_f32_e32 v193, v78
	v_sub_f32_e32 v79, v79, v192
	v_exp_f32_e32 v79, v79
	s_or_b64 vcc, s[62:63], vcc
	v_add_f32_e32 v193, 1.0, v193
	v_log_f32_e32 v193, v193
	v_add_f32_e32 v192, 0, v192
	v_cndmask_b32_e32 v79, 0, v79, vcc
	v_cndmask_b32_e32 v192, 0, v192, vcc
	v_cmp_lt_i32_e32 vcc, v194, v173
	s_or_b64 vcc, s[62:63], vcc
	v_sub_f32_e32 v78, v78, v193
	v_cndmask_b32_e32 v193, 0, v193, vcc
	v_sub_f32_e32 v78, v78, v192
	v_add_f32_e32 v192, v193, v192
	v_exp_f32_e32 v193, v77
	v_exp_f32_e32 v78, v78
	v_add_u32_e32 v194, 0x4d, v175
	v_add_f32_e32 v193, 1.0, v193
	v_log_f32_e32 v193, v193
	v_cndmask_b32_e32 v78, 0, v78, vcc
	v_cmp_lt_i32_e32 vcc, v194, v173
	s_or_b64 vcc, s[62:63], vcc
	v_sub_f32_e32 v77, v77, v193
	v_cndmask_b32_e32 v193, 0, v193, vcc
	v_sub_f32_e32 v77, v77, v192
	v_add_f32_e32 v192, v193, v192
	v_exp_f32_e32 v193, v76
	v_exp_f32_e32 v77, v77
	v_add_u32_e32 v194, 0x4c, v175
	v_add_f32_e32 v193, 1.0, v193
	v_log_f32_e32 v193, v193
	v_cndmask_b32_e32 v77, 0, v77, vcc
	v_cmp_lt_i32_e32 vcc, v194, v173
	s_or_b64 vcc, s[62:63], vcc
	v_sub_f32_e32 v76, v76, v193
	v_cndmask_b32_e32 v193, 0, v193, vcc
	v_sub_f32_e32 v76, v76, v192
	v_add_f32_e32 v192, v193, v192
	v_exp_f32_e32 v193, v75
	v_exp_f32_e32 v76, v76
	v_add_u32_e32 v194, 0x4b, v175
	v_add_f32_e32 v193, 1.0, v193
	v_log_f32_e32 v193, v193
	v_cndmask_b32_e32 v76, 0, v76, vcc
	v_cmp_lt_i32_e32 vcc, v194, v173
	s_or_b64 vcc, s[62:63], vcc
	v_sub_f32_e32 v75, v75, v193
	v_cndmask_b32_e32 v193, 0, v193, vcc
	v_sub_f32_e32 v75, v75, v192
	v_add_f32_e32 v192, v193, v192
	v_exp_f32_e32 v193, v74
	v_exp_f32_e32 v75, v75
	v_add_u32_e32 v194, 0x4a, v175
	v_add_f32_e32 v193, 1.0, v193
	v_log_f32_e32 v193, v193
	v_cndmask_b32_e32 v75, 0, v75, vcc
	v_cmp_lt_i32_e32 vcc, v194, v173
	s_or_b64 vcc, s[62:63], vcc
	v_sub_f32_e32 v74, v74, v193
	v_cndmask_b32_e32 v193, 0, v193, vcc
	v_sub_f32_e32 v74, v74, v192
	v_add_f32_e32 v192, v193, v192
	v_exp_f32_e32 v193, v73
	v_exp_f32_e32 v74, v74
	v_add_u32_e32 v194, 0x49, v175
	v_add_f32_e32 v193, 1.0, v193
	v_log_f32_e32 v193, v193
	v_cndmask_b32_e32 v74, 0, v74, vcc
	v_cmp_lt_i32_e32 vcc, v194, v173
	s_or_b64 vcc, s[62:63], vcc
	v_sub_f32_e32 v73, v73, v193
	v_cndmask_b32_e32 v193, 0, v193, vcc
	v_sub_f32_e32 v73, v73, v192
	v_add_f32_e32 v192, v193, v192
	v_exp_f32_e32 v193, v72
	v_exp_f32_e32 v73, v73
	v_add_u32_e32 v194, 0x48, v175
	v_add_f32_e32 v193, 1.0, v193
	v_log_f32_e32 v193, v193
	v_cndmask_b32_e32 v73, 0, v73, vcc
	v_cmp_lt_i32_e32 vcc, v194, v173
	s_or_b64 vcc, s[62:63], vcc
	v_sub_f32_e32 v72, v72, v193
	v_cndmask_b32_e32 v193, 0, v193, vcc
	v_sub_f32_e32 v72, v72, v192
	v_add_f32_e32 v192, v193, v192
	v_exp_f32_e32 v193, v71
	v_exp_f32_e32 v72, v72
	v_add_u32_e32 v194, 0x47, v175
	v_add_f32_e32 v193, 1.0, v193
; #define LAS __attribute__((address_space(3)))
; __device__ __forceinline__ unsigned pk2(float lo, float hi) { f32x2 v = {lo, hi}; bf16x2_t b = __builtin_convertvector(v, bf16x2_t); return __builtin_bit_cast(unsigned, b); }
; __device__ __forceinline__ void attn_unit(int b, int h, int qb, const bf16_t* __restrict__ QK, const bf16_t* __restrict__ VT, bf16_t* __restrict__ O, const float* __restrict__ qg, const float* __restrict__ kg, ...
;     ...
;                 for (int r = 15; r >= 0; --r) {
;                     const float z = p[kb][r];
;                     const float e = __builtin_amdgcn_exp2f(z);
;                     float sp = __builtin_amdgcn_logf(1.0f + e);
;                     float a = __builtin_amdgcn_exp2f(z - sp - run);
;                     if (needmask && !(s0 + r < tq)) { sp = 0.f; a = 0.f; }
;                     run += sp; p[kb][r] = a; }
;                 T[kb] = run; }
;             const float T0o = __shfl_xor(T[0], 32), T1o = __shfl_xor(T[1], 32);
;             const float base1 = R + (hi == 0 ? T1o : 0.f), base0 = R + T[1] + T1o + (hi == 0 ? T0o : 0.f);
;             const float f0 = __builtin_amdgcn_exp2f(-base0), f1 = __builtin_amdgcn_exp2f(-base1);
;             R += (T[0] + T0o) + (T[1] + T1o);
;             bf16x8 pa[2][2];
; #pragma unroll
;             for (int kb = 0; kb < 2; ++kb) { const float f = kb ? f1 : f0;
; #pragma unroll
;                 for (int s2 = 0; s2 < 2; ++s2) { u32x4 w;
;                     w.x = pk2(p[kb][8 * s2 + 0] * f, p[kb][8 * s2 + 1] * f); w.y = pk2(p[kb][8 * s2 + 2] * f, p[kb][8 * s2 + 3] * f);
;                     w.z = pk2(p[kb][8 * s2 + 4] * f, p[kb][8 * s2 + 5] * f); w.w = pk2(p[kb][8 * s2 + 6] * f, p[kb][8 * s2 + 7] * f);
;                     pa[kb][s2] = __builtin_bit_cast(bf16x8, w); } }
; #pragma unroll
;             for (int d = 0; d < 4; ++d)
; #pragma unroll
;                 for (int kb = 0; kb < 2; ++kb)
; #pragma unroll
;                     for (int s2 = 0; s2 < 2; ++s2) { const bf16x8 vb = *(const LAS bf16x8*)(vb_ + d * 32 * AV_ROWB + kb * 64 + s2 * 16); o[d] = __builtin_amdgcn_mfma_f32_32x32x16_bf16(pa[kb][s2], vb, o[d], 0, 0, 0); }
;             wdone = __all(R >= ATT_DONE_LOG2) != 0;
	v_log_f32_e32 v193, v193
	v_cndmask_b32_e32 v72, 0, v72, vcc
	v_cmp_lt_i32_e32 vcc, v194, v173
	s_or_b64 vcc, s[62:63], vcc
	v_sub_f32_e32 v71, v71, v193
	v_cndmask_b32_e32 v193, 0, v193, vcc
	v_sub_f32_e32 v71, v71, v192
	v_add_f32_e32 v192, v193, v192
	v_exp_f32_e32 v193, v70
	v_exp_f32_e32 v71, v71
	v_add_u32_e32 v194, 0x46, v175
	v_add_f32_e32 v193, 1.0, v193
	v_log_f32_e32 v193, v193
	v_cndmask_b32_e32 v71, 0, v71, vcc
	v_cmp_lt_i32_e32 vcc, v194, v173
	s_or_b64 vcc, s[62:63], vcc
	v_sub_f32_e32 v70, v70, v193
	v_cndmask_b32_e32 v193, 0, v193, vcc
	v_sub_f32_e32 v70, v70, v192
	v_add_f32_e32 v192, v193, v192
	v_exp_f32_e32 v193, v69
	v_exp_f32_e32 v70, v70
	v_add_u32_e32 v194, 0x45, v175
	v_add_f32_e32 v193, 1.0, v193
	v_log_f32_e32 v193, v193
	v_cndmask_b32_e32 v70, 0, v70, vcc
	v_cmp_lt_i32_e32 vcc, v194, v173
	s_or_b64 vcc, s[62:63], vcc
	v_sub_f32_e32 v69, v69, v193
	v_cndmask_b32_e32 v193, 0, v193, vcc
	v_sub_f32_e32 v69, v69, v192
	v_add_f32_e32 v192, v193, v192
	v_exp_f32_e32 v193, v68
	v_exp_f32_e32 v69, v69
	v_add_u32_e32 v194, 0x44, v175
	v_add_f32_e32 v193, 1.0, v193
	v_log_f32_e32 v193, v193
	v_cndmask_b32_e32 v69, 0, v69, vcc
	v_cmp_lt_i32_e32 vcc, v194, v173
	s_or_b64 vcc, s[62:63], vcc
	v_sub_f32_e32 v68, v68, v193
	v_cndmask_b32_e32 v193, 0, v193, vcc
	v_sub_f32_e32 v68, v68, v192
	v_add_f32_e32 v192, v193, v192
	v_exp_f32_e32 v193, v67
	v_exp_f32_e32 v68, v68
	v_add_u32_e32 v194, 0x43, v175
	v_add_f32_e32 v193, 1.0, v193
	v_log_f32_e32 v193, v193
	v_cndmask_b32_e32 v68, 0, v68, vcc
	v_cmp_lt_i32_e32 vcc, v194, v173
	s_or_b64 vcc, s[62:63], vcc
	v_sub_f32_e32 v67, v67, v193
	v_cndmask_b32_e32 v193, 0, v193, vcc
	v_sub_f32_e32 v67, v67, v192
	v_add_f32_e32 v192, v193, v192
	v_exp_f32_e32 v193, v66
	v_exp_f32_e32 v67, v67
	v_add_u32_e32 v194, 0x42, v175
	v_add_u32_e32 v175, 0x41, v175
	v_add_f32_e32 v193, 1.0, v193
	v_log_f32_e32 v193, v193
	v_cndmask_b32_e32 v67, 0, v67, vcc
	v_cmp_lt_i32_e32 vcc, v194, v173
	s_or_b64 vcc, s[62:63], vcc
	v_sub_f32_e32 v66, v66, v193
	v_cndmask_b32_e32 v193, 0, v193, vcc
	v_sub_f32_e32 v66, v66, v192
	v_add_f32_e32 v192, v193, v192
	v_exp_f32_e32 v193, v65
	v_exp_f32_e32 v66, v66
	v_add_f32_e32 v194, v169, v184
	v_add_f32_e32 v193, 1.0, v193
	v_log_f32_e32 v193, v193
	v_cndmask_b32_e32 v66, 0, v66, vcc
	v_cmp_lt_i32_e32 vcc, v175, v173
	s_or_b64 vcc, s[62:63], vcc
	v_sub_f32_e32 v65, v65, v193
	v_cndmask_b32_e32 v175, 0, v193, vcc
	v_sub_f32_e32 v65, v65, v192
	v_add_f32_e32 v175, v175, v192
	v_exp_f32_e32 v192, v64
	v_exp_f32_e32 v65, v65
	v_add_f32_e32 v192, 1.0, v192
	v_log_f32_e32 v192, v192
	v_cndmask_b32_e32 v65, 0, v65, vcc
	v_cmp_lt_i32_e32 vcc, v171, v173
	s_or_b64 vcc, s[62:63], vcc
	v_sub_f32_e32 v64, v64, v192
	v_cndmask_b32_e32 v171, 0, v192, vcc
	v_add_f32_e32 v171, v171, v175
	v_sub_f32_e32 v64, v64, v175
	ds_bpermute_b32 v175, v157, v171
	ds_bpermute_b32 v192, v157, v184
	v_exp_f32_e32 v64, v64
	s_waitcnt lgkmcnt(1)
	v_cndmask_b32_e64 v195, 0, v175, s[4:5]
	s_waitcnt lgkmcnt(0)
	v_add_f32_e32 v194, v194, v192
	v_add_f32_e32 v194, v195, v194
	v_exp_f32_e64 v194, -v194
	v_cndmask_b32_e32 v64, 0, v64, vcc
	v_cndmask_b32_e64 v193, 0, v192, s[4:5]
	v_add_f32_e32 v193, v169, v193
	v_mul_f32_e32 v64, v64, v194
	v_mul_f32_e32 v65, v65, v194
	v_cvt_pk_bf16_f32 v64, v64, v65
	v_mul_f32_e32 v65, v66, v194
	v_mul_f32_e32 v66, v67, v194
	v_cvt_pk_bf16_f32 v65, v65, v66
	v_mul_f32_e32 v66, v68, v194
	v_mul_f32_e32 v67, v69, v194
	v_cvt_pk_bf16_f32 v66, v66, v67
	v_mul_f32_e32 v67, v70, v194
	v_mul_f32_e32 v68, v71, v194
	v_exp_f32_e64 v193, -v193
	v_cvt_pk_bf16_f32 v67, v67, v68
	v_mul_f32_e32 v68, v72, v194
	v_mul_f32_e32 v69, v73, v194
	v_cvt_pk_bf16_f32 v68, v68, v69
	v_mul_f32_e32 v69, v74, v194
	v_mul_f32_e32 v70, v75, v194
	v_cvt_pk_bf16_f32 v69, v69, v70
	v_mul_f32_e32 v70, v76, v194
	v_mul_f32_e32 v71, v77, v194
	v_cvt_pk_bf16_f32 v70, v70, v71
	v_mul_f32_e32 v71, v78, v194
	v_mul_f32_e32 v72, v79, v194
	v_cvt_pk_bf16_f32 v71, v71, v72
	v_mul_f32_e32 v72, v193, v80
	v_mul_f32_e32 v73, v193, v81
	v_cvt_pk_bf16_f32 v76, v72, v73
	v_mul_f32_e32 v72, v193, v82
	v_mul_f32_e32 v73, v193, v83
	v_cvt_pk_bf16_f32 v77, v72, v73
	v_mul_f32_e32 v72, v193, v84
	v_mul_f32_e32 v73, v193, v85
	v_cvt_pk_bf16_f32 v78, v72, v73
	v_mul_f32_e32 v72, v193, v86
	v_mul_f32_e32 v73, v193, v87
	v_cvt_pk_bf16_f32 v79, v72, v73
	v_mul_f32_e32 v72, v193, v88
	v_mul_f32_e32 v73, v193, v89
	v_cvt_pk_bf16_f32 v72, v72, v73
	v_mul_f32_e32 v73, v193, v90
	v_mul_f32_e32 v74, v193, v91
	v_cvt_pk_bf16_f32 v73, v73, v74
	v_mul_f32_e32 v74, v193, v92
	v_mul_f32_e32 v75, v193, v93
	v_cvt_pk_bf16_f32 v74, v74, v75
	v_mul_f32_e32 v75, v193, v94
	v_mul_f32_e32 v80, v193, v95
	v_add_u32_e32 v88, s16, v191
	v_cvt_pk_bf16_f32 v75, v75, v80
	ds_read_b128 v[80:83], v88 offset:34816
	ds_read_b128 v[84:87], v88 offset:34832
	ds_read_b128 v[92:95], v88 offset:34880
	s_waitcnt lgkmcnt(2)
	v_mfma_f32_32x32x16_bf16 v[0:15], v[64:67], v[80:83], v[0:15]
	ds_read_b128 v[80:83], v88 offset:34896
	v_add_f32_e32 v171, v171, v175
	v_add_f32_e32 v175, v184, v192
	v_add_f32_e32 v171, v171, v175
	v_add_f32_e32 v169, v169, v171
	v_cmp_le_f32_e32 vcc, s72, v169
	s_cmp_eq_u64 vcc, exec
	s_waitcnt lgkmcnt(2)
	v_mfma_f32_32x32x16_bf16 v[0:15], v[68:71], v[84:87], v[0:15]
	ds_read_b128 v[84:87], v88 offset:39424
	s_cselect_b64 s[16:17], -1, 0
	s_waitcnt lgkmcnt(2)
	v_mfma_f32_32x32x16_bf16 v[0:15], v[76:79], v[92:95], v[0:15]
	ds_read_b128 v[92:95], v88 offset:39440
	s_waitcnt lgkmcnt(2)
	v_mfma_f32_32x32x16_bf16 v[0:15], v[72:75], v[80:83], v[0:15]
	ds_read_b128 v[80:83], v88 offset:39488
	s_waitcnt lgkmcnt(2)
	v_mfma_f32_32x32x16_bf16 v[48:63], v[64:67], v[84:87], v[48:63]
	ds_read_b128 v[84:87], v88 offset:39504
	s_waitcnt lgkmcnt(2)
	v_mfma_f32_32x32x16_bf16 v[48:63], v[68:71], v[92:95], v[48:63]
	ds_read_b128 v[92:95], v88 offset:44032
	s_waitcnt lgkmcnt(2)
	v_mfma_f32_32x32x16_bf16 v[48:63], v[76:79], v[80:83], v[48:63]
	ds_read_b128 v[80:83], v88 offset:44048
	s_waitcnt lgkmcnt(2)
	v_mfma_f32_32x32x16_bf16 v[48:63], v[72:75], v[84:87], v[48:63]
	ds_read_b128 v[84:87], v88 offset:44096
	s_waitcnt lgkmcnt(2)
	v_mfma_f32_32x32x16_bf16 v[32:47], v[64:67], v[92:95], v[32:47]
	ds_read_b128 v[92:95], v88 offset:44112
	s_waitcnt lgkmcnt(2)
	v_mfma_f32_32x32x16_bf16 v[32:47], v[68:71], v[80:83], v[32:47]
	ds_read_b128 v[80:83], v88 offset:48640
	s_waitcnt lgkmcnt(2)
	v_mfma_f32_32x32x16_bf16 v[32:47], v[76:79], v[84:87], v[32:47]
	ds_read_b128 v[84:87], v88 offset:48656
	s_waitcnt lgkmcnt(2)
	v_mfma_f32_32x32x16_bf16 v[32:47], v[72:75], v[92:95], v[32:47]
	ds_read_b128 v[92:95], v88 offset:48704
	s_waitcnt lgkmcnt(2)
	v_mfma_f32_32x32x16_bf16 v[16:31], v[64:67], v[80:83], v[16:31]
	ds_read_b128 v[80:83], v88 offset:48720
	s_waitcnt lgkmcnt(2)
	v_mfma_f32_32x32x16_bf16 v[16:31], v[68:71], v[84:87], v[16:31]
	s_waitcnt lgkmcnt(1)
	v_mfma_f32_32x32x16_bf16 v[16:31], v[76:79], v[92:95], v[16:31]
	s_waitcnt lgkmcnt(0)
	v_mfma_f32_32x32x16_bf16 v[16:31], v[72:75], v[80:83], v[16:31]
